# attention: last 4 PV MFMAs of each tile deferred into the next tile's softmax phase (12/12 MFMA split), peeled first tile
# speedup vs baseline: 1.0294x; 1.0026x over previous
; #define AT_LOADK(kt) do { _Pragma("unroll") for (int i_ = 0; i_ < 2; ++i_) { const int id_ = tid + 512 * i_; \
;             kr[i_] = *(const u32x4*)(kbase + (size_t)((kt) * 64 + (id_ >> 4)) * 4096 + (id_ & 15) * 8); } } while (0)
; #define AT_LOADV(kt) do { _Pragma("unroll") for (int i_ = 0; i_ < 2; ++i_) { const int id_ = tid + 512 * i_; \
;             vr[i_] = *(const u32x4*)(vbase + (size_t)(id_ >> 3) * 4096 + (kt) * 64 + (id_ & 7) * 8); } } while (0)
; #define AT_STOREK(buf) do { _Pragma("unroll") for (int i_ = 0; i_ < 2; ++i_) { const int id_ = tid + 512 * i_; \
;             *(u32x4*)(sKt + (buf) * 8704 + (id_ >> 4) * 136 + (id_ & 15) * 8) = kr[i_]; } } while (0)
; #define AT_STOREV(buf) do { _Pragma("unroll") for (int i_ = 0; i_ < 2; ++i_) { const int id_ = tid + 512 * i_; \
;             *(u32x4*)(sVt + (buf) * 9216 + (id_ >> 3) * 72 + (id_ & 7) * 8) = vr[i_]; } } while (0)
; __device__ __forceinline__ void phase_attn(const Params& p, unsigned char* lds) {
;     ...
;         AT_LOADK(toff & 63); AT_LOADV(toff & 63); AT_STOREK(0); AT_STOREV(0);
;         __syncthreads();
;         f32x16 st[2];
;         for (int kt = 0; kt < 64; ++kt) {
;             const int buf = kt & 1;
;             if (kt + 1 < 64) { AT_LOADK((kt + 1 + toff) & 63); AT_LOADV((kt + 1 + toff) & 63); }
;             AT_QK(st, buf);
;             float mloc = st[0][0];
; #pragma unroll
;             for (int i = 0; i < 16; ++i) { mloc = fmaxf(mloc, st[0][i]); mloc = fmaxf(mloc, st[1][i]); }
;             mloc = fmaxf(mloc, __shfl_xor(mloc, 32));
;             const float mnew = fmaxf(mrun, mloc);
;             if (__builtin_amdgcn_ballot_w64(mnew > mrun) != 0ull) {
;                 const float alpha = __builtin_amdgcn_exp2f(mrun - mnew);
;                 lsum *= alpha;
; #pragma unroll
;                 for (int vb = 0; vb < 4; ++vb)
; #pragma unroll
;                     for (int i = 0; i < 16; ++i) ot[vb][i] *= alpha;
;             }
;             mrun = mnew;
.LBB0_2021:
	v_add_u32_e32 v147, 0x4800, v159
	s_and_b32 s12, s21, 0xfc0
	v_add_u32_e32 v116, s12, v162
	v_ashrrev_i32_e32 v117, 31, v116
	v_add_u32_e32 v112, s12, v163
	v_lshlrev_b64 v[116:117], 13, v[116:117]
	v_ashrrev_i32_e32 v113, 31, v112
	v_lshl_add_u64 v[116:117], v[152:153], 0, v[116:117]
	v_lshlrev_b64 v[112:113], 13, v[112:113]
	v_lshl_add_u64 v[112:113], v[152:153], 0, v[112:113]
	global_load_dwordx4 v[116:119], v[116:117], off
	global_load_dwordx4 v[112:115], v[112:113], off
	ds_read_b128 v[172:175], v157 offset:0
	ds_read_b128 v[176:179], v157 offset:32
	ds_read_b128 v[180:183], v157 offset:64
	ds_read_b128 v[184:187], v157 offset:96
	ds_read_b128 v[188:191], v157 offset:8704
	ds_read_b128 v[192:195], v157 offset:8736
	ds_read_b128 v[228:231], v157 offset:8768
	ds_read_b128 v[232:235], v157 offset:8800
	s_waitcnt vmcnt(2)
	s_waitcnt lgkmcnt(7)
	v_mfma_f32_32x32x16_bf16 v[80:95], v[172:175], v[108:111], 0
	s_waitcnt lgkmcnt(6)
	v_mfma_f32_32x32x16_bf16 v[80:95], v[176:179], v[104:107], v[80:95]
	s_waitcnt lgkmcnt(5)
	v_mfma_f32_32x32x16_bf16 v[80:95], v[180:183], v[100:103], v[80:95]
	s_waitcnt lgkmcnt(4)
	v_mfma_f32_32x32x16_bf16 v[80:95], v[184:187], v[96:99], v[80:95]
	s_waitcnt lgkmcnt(3)
	v_mfma_f32_32x32x16_bf16 v[64:79], v[188:191], v[108:111], 0
	s_waitcnt lgkmcnt(2)
	v_mfma_f32_32x32x16_bf16 v[64:79], v[192:195], v[104:107], v[64:79]
	s_waitcnt lgkmcnt(1)
	v_mfma_f32_32x32x16_bf16 v[64:79], v[228:231], v[100:103], v[64:79]
	s_waitcnt lgkmcnt(0)
	v_mfma_f32_32x32x16_bf16 v[64:79], v[232:235], v[96:99], v[64:79]
	v_add_u32_e32 v239, v131, v164
	s_waitcnt vmcnt(1)
	ds_write_b128 v239, v[116:119] offset:17408
	v_add_u32_e32 v239, v131, v165
	s_waitcnt vmcnt(0)
	ds_write_b128 v239, v[112:115] offset:17408
	s_nop 7
	s_nop 3
	v_max3_f32 v145, v80, v81, v82
	v_max3_f32 v237, v64, v65, v66
	v_max3_f32 v145, v145, v83, v84
	v_max3_f32 v237, v237, v67, v68
	v_max3_f32 v145, v145, v85, v86
	v_max3_f32 v237, v237, v69, v70
	v_max3_f32 v145, v145, v87, v88
	v_max3_f32 v237, v237, v71, v72
	v_max3_f32 v145, v145, v89, v90
	v_max3_f32 v237, v237, v73, v74
	v_max3_f32 v145, v145, v91, v92
	v_max3_f32 v237, v237, v75, v76
	v_max3_f32 v145, v145, v93, v94
	v_max3_f32 v237, v237, v77, v78
	v_max_f32_e32 v145, v145, v95
	v_max_f32_e32 v237, v237, v79
	v_max_f32_e32 v145, v145, v237
	ds_bpermute_b32 v237, v158, v145
	s_waitcnt lgkmcnt(0)
	v_max3_f32 v145, v149, v145, v237
	v_sub_f32_e32 v238, v149, v145
	v_cmp_gt_f32_e32 vcc, v145, v149
	v_exp_f32_e32 v238, v238
	v_mov_b32_e32 v149, v145
	s_barrier
	ds_read_b128 v[172:175], v157 offset:17408
	ds_read_b128 v[176:179], v157 offset:17440
	ds_read_b128 v[180:183], v157 offset:17472
	ds_read_b128 v[184:187], v157 offset:17504
	ds_read_b128 v[188:191], v157 offset:26112
	ds_read_b128 v[192:195], v157 offset:26144
	ds_read_b128 v[228:231], v157 offset:26176
	ds_read_b128 v[232:235], v157 offset:26208
	s_add_i32 s12, s21, 64
	s_and_b32 s12, s12, 0xfc0
	v_add_u32_e32 v116, s12, v162
	v_ashrrev_i32_e32 v117, 31, v116
	v_add_u32_e32 v112, s12, v163
	v_lshlrev_b64 v[116:117], 13, v[116:117]
	v_ashrrev_i32_e32 v113, 31, v112
	v_lshl_add_u64 v[116:117], v[152:153], 0, v[116:117]
	v_lshlrev_b64 v[112:113], 13, v[112:113]
	v_lshl_add_u64 v[112:113], v[152:153], 0, v[112:113]
	global_load_dwordx4 v[116:119], v[116:117], off
	global_load_dwordx4 v[112:115], v[112:113], off
	s_and_b32 s12, s21, 0xfc0
	s_lshl_b32 s12, s12, 1
	v_lshl_add_u64 v[124:125], v[154:155], 0, s[12:13]
	v_lshl_add_u64 v[120:121], v[124:125], 0, v[138:139]
	v_lshl_add_u64 v[124:125], v[124:125], 0, v[136:137]
	global_load_dwordx4 v[124:127], v[124:125], off
	global_load_dwordx4 v[120:123], v[120:121], off
	s_cbranch_vccz .Lat_norescale_1
	v_pk_mul_f32 v[62:63], v[62:63], v[238:239] op_sel_hi:[1,0]
	v_pk_mul_f32 v[60:61], v[60:61], v[238:239] op_sel_hi:[1,0]
	v_pk_mul_f32 v[58:59], v[58:59], v[238:239] op_sel_hi:[1,0]
	v_pk_mul_f32 v[56:57], v[56:57], v[238:239] op_sel_hi:[1,0]
	v_pk_mul_f32 v[54:55], v[54:55], v[238:239] op_sel_hi:[1,0]
	v_pk_mul_f32 v[52:53], v[52:53], v[238:239] op_sel_hi:[1,0]
	v_pk_mul_f32 v[50:51], v[50:51], v[238:239] op_sel_hi:[1,0]
	v_pk_mul_f32 v[48:49], v[48:49], v[238:239] op_sel_hi:[1,0]
	v_pk_mul_f32 v[46:47], v[46:47], v[238:239] op_sel_hi:[1,0]
	v_pk_mul_f32 v[44:45], v[44:45], v[238:239] op_sel_hi:[1,0]
	v_pk_mul_f32 v[42:43], v[42:43], v[238:239] op_sel_hi:[1,0]
	v_pk_mul_f32 v[40:41], v[40:41], v[238:239] op_sel_hi:[1,0]
	v_pk_mul_f32 v[38:39], v[38:39], v[238:239] op_sel_hi:[1,0]
	v_pk_mul_f32 v[36:37], v[36:37], v[238:239] op_sel_hi:[1,0]
	v_pk_mul_f32 v[34:35], v[34:35], v[238:239] op_sel_hi:[1,0]
	v_pk_mul_f32 v[32:33], v[32:33], v[238:239] op_sel_hi:[1,0]
	v_pk_mul_f32 v[30:31], v[30:31], v[238:239] op_sel_hi:[1,0]
	v_pk_mul_f32 v[28:29], v[28:29], v[238:239] op_sel_hi:[1,0]
	v_pk_mul_f32 v[26:27], v[26:27], v[238:239] op_sel_hi:[1,0]
	v_pk_mul_f32 v[24:25], v[24:25], v[238:239] op_sel_hi:[1,0]
	v_pk_mul_f32 v[22:23], v[22:23], v[238:239] op_sel_hi:[1,0]
	v_pk_mul_f32 v[20:21], v[20:21], v[238:239] op_sel_hi:[1,0]
	v_pk_mul_f32 v[18:19], v[18:19], v[238:239] op_sel_hi:[1,0]
	v_pk_mul_f32 v[16:17], v[16:17], v[238:239] op_sel_hi:[1,0]
	v_pk_mul_f32 v[14:15], v[14:15], v[238:239] op_sel_hi:[1,0]
	v_pk_mul_f32 v[12:13], v[12:13], v[238:239] op_sel_hi:[1,0]
	v_pk_mul_f32 v[10:11], v[10:11], v[238:239] op_sel_hi:[1,0]
	v_pk_mul_f32 v[8:9], v[8:9], v[238:239] op_sel_hi:[1,0]
	v_pk_mul_f32 v[6:7], v[6:7], v[238:239] op_sel_hi:[1,0]
	v_pk_mul_f32 v[4:5], v[4:5], v[238:239] op_sel_hi:[1,0]
	v_pk_mul_f32 v[2:3], v[2:3], v[238:239] op_sel_hi:[1,0]
	v_pk_mul_f32 v[0:1], v[0:1], v[238:239] op_sel_hi:[1,0]
	v_mul_f32_e32 v128, v128, v238
; __device__ __forceinline__ unsigned cvt_pk_bf16(float lo, float hi) { unsigned r; asm volatile("v_cvt_pk_bf16_f32 %0, %1, %2" : "=v"(r) : "v"(lo), "v"(hi)); return r; }
; __device__ __forceinline__ void phase_attn(const Params& p, unsigned char* lds) {
;     ...
;             bf16x8 P[2][2];
; #pragma unroll
;             for (int kb = 0; kb < 2; ++kb)
; #pragma unroll
;                 for (int s2 = 0; s2 < 2; ++s2) { u32x4 pk;
; #pragma unroll
;                     for (int jj = 0; jj < 4; ++jj) { const float p0 = __builtin_amdgcn_exp2f(st[kb][8 * s2 + 2 * jj] - mnew), p1 = __builtin_amdgcn_exp2f(st[kb][8 * s2 + 2 * jj + 1] - mnew); lsum += p0 + p1; pk[jj] = cvt_pk_bf16(p0, p1); }
;                     P[kb][s2] = __builtin_bit_cast(bf16x8, pk); }
.Lat_norescale_1:
	v_mov_b32_e32 v236, 0
	s_waitcnt lgkmcnt(7)
	v_mfma_f32_32x32x16_bf16 v[196:211], v[172:175], v[108:111], 0
	v_sub_f32_e32 v80, v80, v149
	v_sub_f32_e32 v81, v81, v149
	v_exp_f32_e32 v80, v80
	v_exp_f32_e32 v81, v81
	v_add_f32_e32 v128, v128, v80
	v_add_f32_e32 v236, v236, v81
	v_cvt_pk_bf16_f32 v80, v80, v81
	v_sub_f32_e32 v82, v82, v149
	v_sub_f32_e32 v83, v83, v149
	v_exp_f32_e32 v82, v82
	v_exp_f32_e32 v83, v83
	v_add_f32_e32 v128, v128, v82
	v_add_f32_e32 v236, v236, v83
	v_cvt_pk_bf16_f32 v81, v82, v83
	s_waitcnt lgkmcnt(6)
	v_mfma_f32_32x32x16_bf16 v[196:211], v[176:179], v[104:107], v[196:211]
	v_sub_f32_e32 v84, v84, v149
	v_sub_f32_e32 v85, v85, v149
	v_exp_f32_e32 v84, v84
	v_exp_f32_e32 v85, v85
	v_add_f32_e32 v128, v128, v84
	v_add_f32_e32 v236, v236, v85
	v_cvt_pk_bf16_f32 v82, v84, v85
	v_sub_f32_e32 v86, v86, v149
	v_sub_f32_e32 v87, v87, v149
	v_exp_f32_e32 v86, v86
	v_exp_f32_e32 v87, v87
	v_add_f32_e32 v128, v128, v86
	v_add_f32_e32 v236, v236, v87
	v_cvt_pk_bf16_f32 v83, v86, v87
	s_waitcnt lgkmcnt(5)
	v_mfma_f32_32x32x16_bf16 v[196:211], v[180:183], v[100:103], v[196:211]
	v_sub_f32_e32 v88, v88, v149
	v_sub_f32_e32 v89, v89, v149
	v_exp_f32_e32 v88, v88
	v_exp_f32_e32 v89, v89
	v_add_f32_e32 v128, v128, v88
	v_add_f32_e32 v236, v236, v89
	v_cvt_pk_bf16_f32 v84, v88, v89
	v_sub_f32_e32 v90, v90, v149
	v_sub_f32_e32 v91, v91, v149
	v_exp_f32_e32 v90, v90
	v_exp_f32_e32 v91, v91
	v_add_f32_e32 v128, v128, v90
	v_add_f32_e32 v236, v236, v91
	v_cvt_pk_bf16_f32 v85, v90, v91
	s_waitcnt lgkmcnt(4)
	v_mfma_f32_32x32x16_bf16 v[196:211], v[184:187], v[96:99], v[196:211]
	ds_read_b128 v[172:175], v159 offset:34816
	ds_read_b128 v[176:179], v159 offset:34848
	ds_read_b128 v[180:183], v159 offset:34880
	ds_read_b128 v[184:187], v159 offset:34912
	v_sub_f32_e32 v92, v92, v149
	v_sub_f32_e32 v93, v93, v149
	v_exp_f32_e32 v92, v92
	v_exp_f32_e32 v93, v93
	v_add_f32_e32 v128, v128, v92
	v_add_f32_e32 v236, v236, v93
	v_cvt_pk_bf16_f32 v86, v92, v93
	v_sub_f32_e32 v94, v94, v149
	v_sub_f32_e32 v95, v95, v149
	v_exp_f32_e32 v94, v94
	v_exp_f32_e32 v95, v95
	v_add_f32_e32 v128, v128, v94
	v_add_f32_e32 v236, v236, v95
	v_cvt_pk_bf16_f32 v87, v94, v95
	s_waitcnt lgkmcnt(7)
	v_mfma_f32_32x32x16_bf16 v[212:227], v[188:191], v[108:111], 0
	v_sub_f32_e32 v64, v64, v149
	v_sub_f32_e32 v65, v65, v149
	v_exp_f32_e32 v64, v64
	v_exp_f32_e32 v65, v65
	v_add_f32_e32 v128, v128, v64
	v_add_f32_e32 v236, v236, v65
	v_cvt_pk_bf16_f32 v64, v64, v65
	v_sub_f32_e32 v66, v66, v149
	v_sub_f32_e32 v67, v67, v149
	v_exp_f32_e32 v66, v66
	v_exp_f32_e32 v67, v67
	v_add_f32_e32 v128, v128, v66
	v_add_f32_e32 v236, v236, v67
	v_cvt_pk_bf16_f32 v65, v66, v67
	s_waitcnt lgkmcnt(6)
	v_mfma_f32_32x32x16_bf16 v[212:227], v[192:195], v[104:107], v[212:227]
	v_sub_f32_e32 v68, v68, v149
	v_sub_f32_e32 v69, v69, v149
	v_exp_f32_e32 v68, v68
	v_exp_f32_e32 v69, v69
	v_add_f32_e32 v128, v128, v68
	v_add_f32_e32 v236, v236, v69
	v_cvt_pk_bf16_f32 v66, v68, v69
	v_sub_f32_e32 v70, v70, v149
	v_sub_f32_e32 v71, v71, v149
	v_exp_f32_e32 v70, v70
	v_exp_f32_e32 v71, v71
	v_add_f32_e32 v128, v128, v70
	v_add_f32_e32 v236, v236, v71
	v_cvt_pk_bf16_f32 v67, v70, v71
	s_waitcnt lgkmcnt(5)
	v_mfma_f32_32x32x16_bf16 v[212:227], v[228:231], v[100:103], v[212:227]
	v_sub_f32_e32 v72, v72, v149
	v_sub_f32_e32 v73, v73, v149
	v_exp_f32_e32 v72, v72
	v_exp_f32_e32 v73, v73
	v_add_f32_e32 v128, v128, v72
	v_add_f32_e32 v236, v236, v73
	v_cvt_pk_bf16_f32 v68, v72, v73
	v_sub_f32_e32 v74, v74, v149
	v_sub_f32_e32 v75, v75, v149
	v_exp_f32_e32 v74, v74
	v_exp_f32_e32 v75, v75
	v_add_f32_e32 v128, v128, v74
	v_add_f32_e32 v236, v236, v75
	v_cvt_pk_bf16_f32 v69, v74, v75
	s_waitcnt lgkmcnt(4)
; #define AT_LDV(set, vb) do { _Pragma("unroll") for (int kb = 0; kb < 2; ++kb) _Pragma("unroll") for (int s2 = 0; s2 < 2; ++s2) \
;                     vf[set][kb * 2 + s2] = *(const bf16x8*)(sVt + buf * 9216 + (32 * (vb) + ql) * 72 + 32 * kb + 16 * s2 + 8 * g); } while (0)
; __device__ __forceinline__ void phase_attn(const Params& p, unsigned char* lds) {
;     ...
;             float mloc = st[0][0];
; #pragma unroll
;             for (int i = 0; i < 16; ++i) { mloc = fmaxf(mloc, st[0][i]); mloc = fmaxf(mloc, st[1][i]); }
;             mloc = fmaxf(mloc, __shfl_xor(mloc, 32));
;             const float mnew = fmaxf(mrun, mloc);
;             if (__builtin_amdgcn_ballot_w64(mnew > mrun) != 0ull) {
;                 const float alpha = __builtin_amdgcn_exp2f(mrun - mnew);
;                 lsum *= alpha;
; #pragma unroll
;                 for (int vb = 0; vb < 4; ++vb)
; #pragma unroll
;                     for (int i = 0; i < 16; ++i) ot[vb][i] *= alpha;
;             }
;             mrun = mnew;
;     ...
;             {
;                 bf16x8 vf[2][4];
;     ...
;                 AT_LDV(0, 0);
; #pragma unroll
;                 for (int vb = 0; vb < 4; ++vb) {
;                     if (vb < 3) AT_LDV((vb + 1) & 1, vb + 1);
;                     __builtin_amdgcn_sched_barrier(0);
;                     __builtin_amdgcn_s_setprio(2);
; #pragma unroll
;                     for (int kb = 0; kb < 2; ++kb)
; #pragma unroll
;                         for (int s2 = 0; s2 < 2; ++s2) ot[vb] = __builtin_amdgcn_mfma_f32_32x32x16_bf16(vf[vb & 1][kb * 2 + s2], P[kb][s2], ot[vb], 0, 0, 0);
;                     __builtin_amdgcn_s_setprio(0);
;                     __builtin_amdgcn_sched_barrier(0);
;                 }
	v_mfma_f32_32x32x16_bf16 v[212:227], v[232:235], v[96:99], v[212:227]
	ds_read_b128 v[188:191], v159 offset:39424
	ds_read_b128 v[192:195], v159 offset:39456
	ds_read_b128 v[228:231], v159 offset:39488
	ds_read_b128 v[232:235], v159 offset:39520
	v_sub_f32_e32 v76, v76, v149
	v_sub_f32_e32 v77, v77, v149
	v_exp_f32_e32 v76, v76
	v_exp_f32_e32 v77, v77
	v_add_f32_e32 v128, v128, v76
	v_add_f32_e32 v236, v236, v77
	v_cvt_pk_bf16_f32 v70, v76, v77
	v_sub_f32_e32 v78, v78, v149
	v_sub_f32_e32 v79, v79, v149
	v_exp_f32_e32 v78, v78
	v_exp_f32_e32 v79, v79
	v_add_f32_e32 v128, v128, v78
	v_add_f32_e32 v236, v236, v79
	v_cvt_pk_bf16_f32 v71, v78, v79
	v_add_f32_e32 v128, v128, v236
	s_waitcnt lgkmcnt(7)
	v_mfma_f32_32x32x16_bf16 v[48:63], v[172:175], v[80:83], v[48:63]
	s_waitcnt lgkmcnt(6)
	v_mfma_f32_32x32x16_bf16 v[48:63], v[176:179], v[84:87], v[48:63]
	v_max3_f32 v145, v196, v197, v198
	v_max3_f32 v237, v212, v213, v214
	v_max3_f32 v145, v145, v199, v200
	s_waitcnt lgkmcnt(5)
	v_mfma_f32_32x32x16_bf16 v[48:63], v[180:183], v[64:67], v[48:63]
	v_max3_f32 v237, v237, v215, v216
	v_max3_f32 v145, v145, v201, v202
	v_max3_f32 v237, v237, v217, v218
	s_waitcnt lgkmcnt(4)
	v_mfma_f32_32x32x16_bf16 v[48:63], v[184:187], v[68:71], v[48:63]
	v_max3_f32 v145, v145, v203, v204
	v_max3_f32 v237, v237, v219, v220
	v_max3_f32 v145, v145, v205, v206
	ds_read_b128 v[172:175], v159 offset:44032
	ds_read_b128 v[176:179], v159 offset:44064
	ds_read_b128 v[180:183], v159 offset:44096
	ds_read_b128 v[184:187], v159 offset:44128
	s_waitcnt lgkmcnt(7)
	v_mfma_f32_32x32x16_bf16 v[32:47], v[188:191], v[80:83], v[32:47]
	v_max3_f32 v237, v237, v221, v222
	v_max3_f32 v145, v145, v207, v208
	v_max3_f32 v237, v237, v223, v224
	s_waitcnt lgkmcnt(6)
	v_mfma_f32_32x32x16_bf16 v[32:47], v[192:195], v[84:87], v[32:47]
	v_max3_f32 v145, v145, v209, v210
	v_max3_f32 v237, v237, v225, v226
	v_max_f32_e32 v145, v145, v211
	s_waitcnt lgkmcnt(5)
	v_mfma_f32_32x32x16_bf16 v[32:47], v[228:231], v[64:67], v[32:47]
	v_max_f32_e32 v237, v237, v227
	v_max_f32_e32 v145, v145, v237
	ds_bpermute_b32 v237, v158, v145
	s_waitcnt lgkmcnt(5)
	v_mfma_f32_32x32x16_bf16 v[32:47], v[232:235], v[68:71], v[32:47]
	v_add_u32_e32 v239, v131, v164
	s_waitcnt vmcnt(3)
	ds_write_b128 v239, v[116:119] offset:0
	ds_read_b128 v[188:191], v159 offset:48640
	ds_read_b128 v[192:195], v159 offset:48672
	ds_read_b128 v[228:231], v159 offset:48704
	ds_read_b128 v[232:235], v159 offset:48736
	s_waitcnt lgkmcnt(9)
	v_mfma_f32_32x32x16_bf16 v[16:31], v[172:175], v[80:83], v[16:31]
	v_add_u32_e32 v239, v131, v165
	s_waitcnt vmcnt(2)
	ds_write_b128 v239, v[112:115] offset:0
	s_waitcnt lgkmcnt(9)
	v_mfma_f32_32x32x16_bf16 v[16:31], v[176:179], v[84:87], v[16:31]
	v_add_u32_e32 v239, v156, v166
	s_waitcnt vmcnt(1)
	ds_write_b128 v239, v[124:127] offset:53248
	s_waitcnt lgkmcnt(9)
	v_mfma_f32_32x32x16_bf16 v[16:31], v[180:183], v[64:67], v[16:31]
	v_add_u32_e32 v239, v156, v167
	s_waitcnt vmcnt(0)
	ds_write_b128 v239, v[120:123] offset:53248
	s_waitcnt lgkmcnt(9)
	v_mfma_f32_32x32x16_bf16 v[16:31], v[184:187], v[68:71], v[16:31]
	s_waitcnt lgkmcnt(8)
	v_max_f32_e32 v237, v145, v237
	v_add_f32_e32 v239, 0x41000000, v149
	v_max_f32_e32 v145, v149, v237
	v_sub_f32_e32 v238, v149, v145
	v_cmp_gt_f32_e32 vcc, v237, v239
	v_exp_f32_e32 v238, v238
	s_cbranch_vccz .Lat_keepm_2
	v_mov_b32_e32 v149, v145

; __device__ __forceinline__ unsigned cvt_pk_bf16(float lo, float hi) { unsigned r; asm volatile("v_cvt_pk_bf16_f32 %0, %1, %2" : "=v"(r) : "v"(lo), "v"(hi)); return r; }
; #define AT_LOADK(kt) do { _Pragma("unroll") for (int i_ = 0; i_ < 2; ++i_) { const int id_ = tid + 512 * i_; \
;             kr[i_] = *(const u32x4*)(kbase + (size_t)((kt) * 64 + (id_ >> 4)) * 4096 + (id_ & 15) * 8); } } while (0)
; __device__ __forceinline__ void phase_attn(const Params& p, unsigned char* lds) {
;     ...
;             if (kt + 1 < 64) { AT_LOADK((kt + 1 + toff) & 63); AT_LOADV((kt + 1 + toff) & 63); }
;             AT_QK(st, buf);
;             float mloc = st[0][0];
; #pragma unroll
;             for (int i = 0; i < 16; ++i) { mloc = fmaxf(mloc, st[0][i]); mloc = fmaxf(mloc, st[1][i]); }
;             mloc = fmaxf(mloc, __shfl_xor(mloc, 32));
;             const float mnew = fmaxf(mrun, mloc);
;             if (__builtin_amdgcn_ballot_w64(mnew > mrun) != 0ull) {
;                 const float alpha = __builtin_amdgcn_exp2f(mrun - mnew);
;                 lsum *= alpha;
; #pragma unroll
;                 for (int vb = 0; vb < 4; ++vb)
; #pragma unroll
;                     for (int i = 0; i < 16; ++i) ot[vb][i] *= alpha;
;             }
;             mrun = mnew;
;             bf16x8 P[2][2];
; #pragma unroll
;             for (int kb = 0; kb < 2; ++kb)
; #pragma unroll
;                 for (int s2 = 0; s2 < 2; ++s2) { u32x4 pk;
; #pragma unroll
;                     for (int jj = 0; jj < 4; ++jj) { const float p0 = __builtin_amdgcn_exp2f(st[kb][8 * s2 + 2 * jj] - mnew), p1 = __builtin_amdgcn_exp2f(st[kb][8 * s2 + 2 * jj + 1] - mnew); lsum += p0 + p1; pk[jj] = cvt_pk_bf16(p0, p1); }
;                     P[kb][s2] = __builtin_bit_cast(bf16x8, pk); }
;             {
;                 bf16x8 vf[2][4];
;     ...
;                 AT_LDV(0, 0);
; #pragma unroll
;                 for (int vb = 0; vb < 4; ++vb) {
;                     if (vb < 3) AT_LDV((vb + 1) & 1, vb + 1);
;                     __builtin_amdgcn_sched_barrier(0);
;                     __builtin_amdgcn_s_setprio(2);
; #pragma unroll
;                     for (int kb = 0; kb < 2; ++kb)
; #pragma unroll
;                         for (int s2 = 0; s2 < 2; ++s2) ot[vb] = __builtin_amdgcn_mfma_f32_32x32x16_bf16(vf[vb & 1][kb * 2 + s2], P[kb][s2], ot[vb], 0, 0, 0);
.Lat_loop:
	ds_read_b128 v[172:175], v157 offset:0
	ds_read_b128 v[176:179], v157 offset:32
	ds_read_b128 v[180:183], v157 offset:64
	ds_read_b128 v[184:187], v157 offset:96
	s_add_i32 s12, s21, 64
	s_and_b32 s12, s12, 0xfc0
	v_add_u32_e32 v116, s12, v162
	v_ashrrev_i32_e32 v117, 31, v116
	v_add_u32_e32 v112, s12, v163
	v_lshlrev_b64 v[116:117], 13, v[116:117]
	v_ashrrev_i32_e32 v113, 31, v112
	v_lshl_add_u64 v[116:117], v[152:153], 0, v[116:117]
	v_lshlrev_b64 v[112:113], 13, v[112:113]
	v_lshl_add_u64 v[112:113], v[152:153], 0, v[112:113]
	global_load_dwordx4 v[116:119], v[116:117], off
	global_load_dwordx4 v[112:115], v[112:113], off
	s_and_b32 s12, s21, 0xfc0
	s_lshl_b32 s12, s12, 1
	v_lshl_add_u64 v[124:125], v[154:155], 0, s[12:13]
	v_lshl_add_u64 v[120:121], v[124:125], 0, v[138:139]
	v_lshl_add_u64 v[124:125], v[124:125], 0, v[136:137]
	global_load_dwordx4 v[124:127], v[124:125], off
	global_load_dwordx4 v[120:123], v[120:121], off
	s_cbranch_vccz .Lat_norescale_3
	v_pk_mul_f32 v[62:63], v[62:63], v[238:239] op_sel_hi:[1,0]
	v_pk_mul_f32 v[60:61], v[60:61], v[238:239] op_sel_hi:[1,0]
	v_pk_mul_f32 v[58:59], v[58:59], v[238:239] op_sel_hi:[1,0]
	v_pk_mul_f32 v[56:57], v[56:57], v[238:239] op_sel_hi:[1,0]
	v_pk_mul_f32 v[54:55], v[54:55], v[238:239] op_sel_hi:[1,0]
	v_pk_mul_f32 v[52:53], v[52:53], v[238:239] op_sel_hi:[1,0]
	v_pk_mul_f32 v[50:51], v[50:51], v[238:239] op_sel_hi:[1,0]
	v_pk_mul_f32 v[48:49], v[48:49], v[238:239] op_sel_hi:[1,0]
	v_pk_mul_f32 v[46:47], v[46:47], v[238:239] op_sel_hi:[1,0]
	v_pk_mul_f32 v[44:45], v[44:45], v[238:239] op_sel_hi:[1,0]
	v_pk_mul_f32 v[42:43], v[42:43], v[238:239] op_sel_hi:[1,0]
	v_pk_mul_f32 v[40:41], v[40:41], v[238:239] op_sel_hi:[1,0]
	v_pk_mul_f32 v[38:39], v[38:39], v[238:239] op_sel_hi:[1,0]
	v_pk_mul_f32 v[36:37], v[36:37], v[238:239] op_sel_hi:[1,0]
	v_pk_mul_f32 v[34:35], v[34:35], v[238:239] op_sel_hi:[1,0]
	v_pk_mul_f32 v[32:33], v[32:33], v[238:239] op_sel_hi:[1,0]
	v_pk_mul_f32 v[30:31], v[30:31], v[238:239] op_sel_hi:[1,0]
	v_pk_mul_f32 v[28:29], v[28:29], v[238:239] op_sel_hi:[1,0]
	v_pk_mul_f32 v[26:27], v[26:27], v[238:239] op_sel_hi:[1,0]
	v_pk_mul_f32 v[24:25], v[24:25], v[238:239] op_sel_hi:[1,0]
	v_pk_mul_f32 v[22:23], v[22:23], v[238:239] op_sel_hi:[1,0]
	v_pk_mul_f32 v[20:21], v[20:21], v[238:239] op_sel_hi:[1,0]
	v_pk_mul_f32 v[18:19], v[18:19], v[238:239] op_sel_hi:[1,0]
	v_pk_mul_f32 v[16:17], v[16:17], v[238:239] op_sel_hi:[1,0]
	v_mul_f32_e32 v128, v128, v238
.Lat_norescale_3:
	v_mov_b32_e32 v236, 0
	v_mfma_f32_32x32x16_bf16 v[0:15], v[188:191], v[80:83], v[0:15]
	v_sub_f32_e32 v196, v196, v149
	v_sub_f32_e32 v197, v197, v149
	v_exp_f32_e32 v196, v196
	v_exp_f32_e32 v197, v197
	v_add_f32_e32 v128, v128, v196
	v_add_f32_e32 v236, v236, v197
	v_cvt_pk_bf16_f32 v196, v196, v197
	v_sub_f32_e32 v198, v198, v149
	v_sub_f32_e32 v199, v199, v149
	v_exp_f32_e32 v198, v198
	v_exp_f32_e32 v199, v199
	v_add_f32_e32 v128, v128, v198
	v_add_f32_e32 v236, v236, v199
	v_cvt_pk_bf16_f32 v197, v198, v199
	v_mfma_f32_32x32x16_bf16 v[0:15], v[192:195], v[84:87], v[0:15]
	v_sub_f32_e32 v200, v200, v149
	v_sub_f32_e32 v201, v201, v149
	v_exp_f32_e32 v200, v200
	v_exp_f32_e32 v201, v201
	v_add_f32_e32 v128, v128, v200
	v_add_f32_e32 v236, v236, v201
	v_cvt_pk_bf16_f32 v198, v200, v201
	v_sub_f32_e32 v202, v202, v149
	v_sub_f32_e32 v203, v203, v149
	v_exp_f32_e32 v202, v202
	v_exp_f32_e32 v203, v203
	v_add_f32_e32 v128, v128, v202
	v_add_f32_e32 v236, v236, v203
	v_cvt_pk_bf16_f32 v199, v202, v203
	v_mfma_f32_32x32x16_bf16 v[0:15], v[228:231], v[64:67], v[0:15]
	v_sub_f32_e32 v204, v204, v149
	v_sub_f32_e32 v205, v205, v149
	v_exp_f32_e32 v204, v204
	v_exp_f32_e32 v205, v205
	v_add_f32_e32 v128, v128, v204
	v_add_f32_e32 v236, v236, v205
	v_cvt_pk_bf16_f32 v200, v204, v205
	v_sub_f32_e32 v206, v206, v149
	v_sub_f32_e32 v207, v207, v149
	v_exp_f32_e32 v206, v206
	v_exp_f32_e32 v207, v207
	v_add_f32_e32 v128, v128, v206
	v_add_f32_e32 v236, v236, v207
	v_cvt_pk_bf16_f32 v201, v206, v207
	v_mfma_f32_32x32x16_bf16 v[0:15], v[232:235], v[68:71], v[0:15]
	ds_read_b128 v[188:191], v157 offset:8704
	ds_read_b128 v[192:195], v157 offset:8736
	ds_read_b128 v[228:231], v157 offset:8768
	ds_read_b128 v[232:235], v157 offset:8800
	v_sub_f32_e32 v208, v208, v149
	v_sub_f32_e32 v209, v209, v149
	v_exp_f32_e32 v208, v208
	v_exp_f32_e32 v209, v209
	v_add_f32_e32 v128, v128, v208
	v_add_f32_e32 v236, v236, v209
	v_cvt_pk_bf16_f32 v202, v208, v209
	v_sub_f32_e32 v210, v210, v149
	v_sub_f32_e32 v211, v211, v149
	v_exp_f32_e32 v210, v210
	v_exp_f32_e32 v211, v211
	v_add_f32_e32 v128, v128, v210
	v_add_f32_e32 v236, v236, v211
	v_cvt_pk_bf16_f32 v203, v210, v211
	s_waitcnt lgkmcnt(7)
	v_mfma_f32_32x32x16_bf16 v[80:95], v[172:175], v[108:111], 0
	v_sub_f32_e32 v212, v212, v149
	v_sub_f32_e32 v213, v213, v149
	v_exp_f32_e32 v212, v212
	v_exp_f32_e32 v213, v213
	v_add_f32_e32 v128, v128, v212
	v_add_f32_e32 v236, v236, v213
	v_cvt_pk_bf16_f32 v212, v212, v213
	s_waitcnt lgkmcnt(6)
	v_mfma_f32_32x32x16_bf16 v[80:95], v[176:179], v[104:107], v[80:95]
	v_sub_f32_e32 v214, v214, v149
	v_sub_f32_e32 v215, v215, v149
	v_exp_f32_e32 v214, v214
	v_exp_f32_e32 v215, v215
	v_add_f32_e32 v128, v128, v214
	v_add_f32_e32 v236, v236, v215
	v_cvt_pk_bf16_f32 v213, v214, v215
	s_cbranch_vccz .Lat_norescale_4
	v_pk_mul_f32 v[14:15], v[14:15], v[238:239] op_sel_hi:[1,0]
	v_pk_mul_f32 v[12:13], v[12:13], v[238:239] op_sel_hi:[1,0]
	v_pk_mul_f32 v[10:11], v[10:11], v[238:239] op_sel_hi:[1,0]
	v_pk_mul_f32 v[8:9], v[8:9], v[238:239] op_sel_hi:[1,0]
	v_pk_mul_f32 v[6:7], v[6:7], v[238:239] op_sel_hi:[1,0]
	v_pk_mul_f32 v[4:5], v[4:5], v[238:239] op_sel_hi:[1,0]
	v_pk_mul_f32 v[2:3], v[2:3], v[238:239] op_sel_hi:[1,0]
	v_pk_mul_f32 v[0:1], v[0:1], v[238:239] op_sel_hi:[1,0]
; __device__ __forceinline__ unsigned cvt_pk_bf16(float lo, float hi) { unsigned r; asm volatile("v_cvt_pk_bf16_f32 %0, %1, %2" : "=v"(r) : "v"(lo), "v"(hi)); return r; }
; #define AT_LDV(set, vb) do { _Pragma("unroll") for (int kb = 0; kb < 2; ++kb) _Pragma("unroll") for (int s2 = 0; s2 < 2; ++s2) \
;                     vf[set][kb * 2 + s2] = *(const bf16x8*)(sVt + buf * 9216 + (32 * (vb) + ql) * 72 + 32 * kb + 16 * s2 + 8 * g); } while (0)
; __device__ __forceinline__ void phase_attn(const Params& p, unsigned char* lds) {
;     ...
;             float mloc = st[0][0];
; #pragma unroll
;             for (int i = 0; i < 16; ++i) { mloc = fmaxf(mloc, st[0][i]); mloc = fmaxf(mloc, st[1][i]); }
;             mloc = fmaxf(mloc, __shfl_xor(mloc, 32));
;             const float mnew = fmaxf(mrun, mloc);
;             if (__builtin_amdgcn_ballot_w64(mnew > mrun) != 0ull) {
;                 const float alpha = __builtin_amdgcn_exp2f(mrun - mnew);
;                 lsum *= alpha;
; #pragma unroll
;                 for (int vb = 0; vb < 4; ++vb)
; #pragma unroll
;                     for (int i = 0; i < 16; ++i) ot[vb][i] *= alpha;
;             }
;             mrun = mnew;
;             bf16x8 P[2][2];
; #pragma unroll
;             for (int kb = 0; kb < 2; ++kb)
; #pragma unroll
;                 for (int s2 = 0; s2 < 2; ++s2) { u32x4 pk;
; #pragma unroll
;                     for (int jj = 0; jj < 4; ++jj) { const float p0 = __builtin_amdgcn_exp2f(st[kb][8 * s2 + 2 * jj] - mnew), p1 = __builtin_amdgcn_exp2f(st[kb][8 * s2 + 2 * jj + 1] - mnew); lsum += p0 + p1; pk[jj] = cvt_pk_bf16(p0, p1); }
;                     P[kb][s2] = __builtin_bit_cast(bf16x8, pk); }
;             {
;                 bf16x8 vf[2][4];
;     ...
;                 AT_LDV(0, 0);
; #pragma unroll
;                 for (int vb = 0; vb < 4; ++vb) {
;                     if (vb < 3) AT_LDV((vb + 1) & 1, vb + 1);
;                     __builtin_amdgcn_sched_barrier(0);
;                     __builtin_amdgcn_s_setprio(2);
; #pragma unroll
;                     for (int kb = 0; kb < 2; ++kb)
; #pragma unroll
;                         for (int s2 = 0; s2 < 2; ++s2) ot[vb] = __builtin_amdgcn_mfma_f32_32x32x16_bf16(vf[vb & 1][kb * 2 + s2], P[kb][s2], ot[vb], 0, 0, 0);
;                     __builtin_amdgcn_s_setprio(0);
;                     __builtin_amdgcn_sched_barrier(0);
;                 }
.Lat_norescale_4:
	s_waitcnt lgkmcnt(5)
	v_mfma_f32_32x32x16_bf16 v[80:95], v[180:183], v[100:103], v[80:95]
	v_sub_f32_e32 v216, v216, v149
	v_sub_f32_e32 v217, v217, v149
	v_exp_f32_e32 v216, v216
	v_exp_f32_e32 v217, v217
	v_add_f32_e32 v128, v128, v216
	v_add_f32_e32 v236, v236, v217
	v_cvt_pk_bf16_f32 v214, v216, v217
	s_waitcnt lgkmcnt(4)
	v_mfma_f32_32x32x16_bf16 v[80:95], v[184:187], v[96:99], v[80:95]
	ds_read_b128 v[172:175], v147 offset:34816
	ds_read_b128 v[176:179], v147 offset:34848
	ds_read_b128 v[180:183], v147 offset:34880
	ds_read_b128 v[184:187], v147 offset:34912
	v_sub_f32_e32 v218, v218, v149
	v_sub_f32_e32 v219, v219, v149
	v_exp_f32_e32 v218, v218
	v_exp_f32_e32 v219, v219
	v_add_f32_e32 v128, v128, v218
	v_add_f32_e32 v236, v236, v219
	v_cvt_pk_bf16_f32 v215, v218, v219
	s_waitcnt lgkmcnt(7)
	v_mfma_f32_32x32x16_bf16 v[64:79], v[188:191], v[108:111], 0
	v_sub_f32_e32 v220, v220, v149
	v_sub_f32_e32 v221, v221, v149
	v_exp_f32_e32 v220, v220
	v_exp_f32_e32 v221, v221
	v_add_f32_e32 v128, v128, v220
	v_add_f32_e32 v236, v236, v221
	v_cvt_pk_bf16_f32 v216, v220, v221
	s_waitcnt lgkmcnt(6)
	v_mfma_f32_32x32x16_bf16 v[64:79], v[192:195], v[104:107], v[64:79]
	v_sub_f32_e32 v222, v222, v149
	v_sub_f32_e32 v223, v223, v149
	v_exp_f32_e32 v222, v222
	v_exp_f32_e32 v223, v223
	v_add_f32_e32 v128, v128, v222
	v_add_f32_e32 v236, v236, v223
	v_cvt_pk_bf16_f32 v217, v222, v223
	s_waitcnt lgkmcnt(5)
	v_mfma_f32_32x32x16_bf16 v[64:79], v[228:231], v[100:103], v[64:79]
	v_sub_f32_e32 v224, v224, v149
	v_sub_f32_e32 v225, v225, v149
	v_exp_f32_e32 v224, v224
	v_exp_f32_e32 v225, v225
	v_add_f32_e32 v128, v128, v224
	v_add_f32_e32 v236, v236, v225
	v_cvt_pk_bf16_f32 v218, v224, v225
	s_waitcnt lgkmcnt(4)
	v_mfma_f32_32x32x16_bf16 v[64:79], v[232:235], v[96:99], v[64:79]
	ds_read_b128 v[188:191], v147 offset:39424
	ds_read_b128 v[192:195], v147 offset:39456
	ds_read_b128 v[228:231], v147 offset:39488
	ds_read_b128 v[232:235], v147 offset:39520
	v_sub_f32_e32 v226, v226, v149
	v_sub_f32_e32 v227, v227, v149
	v_exp_f32_e32 v226, v226
	v_exp_f32_e32 v227, v227
	v_add_f32_e32 v128, v128, v226
	v_add_f32_e32 v236, v236, v227
	v_cvt_pk_bf16_f32 v219, v226, v227
	v_add_f32_e32 v128, v128, v236
	s_waitcnt lgkmcnt(7)
	v_mfma_f32_32x32x16_bf16 v[48:63], v[172:175], v[196:199], v[48:63]
	s_waitcnt lgkmcnt(6)
	v_mfma_f32_32x32x16_bf16 v[48:63], v[176:179], v[200:203], v[48:63]
	v_max3_f32 v145, v80, v81, v82
	v_max3_f32 v237, v64, v65, v66
	v_max3_f32 v145, v145, v83, v84
	s_waitcnt lgkmcnt(5)
	v_mfma_f32_32x32x16_bf16 v[48:63], v[180:183], v[212:215], v[48:63]
	v_max3_f32 v237, v237, v67, v68
	v_max3_f32 v145, v145, v85, v86
	v_max3_f32 v237, v237, v69, v70
	s_waitcnt lgkmcnt(4)
	v_mfma_f32_32x32x16_bf16 v[48:63], v[184:187], v[216:219], v[48:63]
	v_max3_f32 v145, v145, v87, v88
	v_max3_f32 v237, v237, v71, v72
	v_max3_f32 v145, v145, v89, v90
	ds_read_b128 v[172:175], v147 offset:44032
	ds_read_b128 v[176:179], v147 offset:44064
	ds_read_b128 v[180:183], v147 offset:44096
	ds_read_b128 v[184:187], v147 offset:44128
	s_waitcnt lgkmcnt(7)
	v_mfma_f32_32x32x16_bf16 v[32:47], v[188:191], v[196:199], v[32:47]
	v_max3_f32 v237, v237, v73, v74
	v_max3_f32 v145, v145, v91, v92
	v_max3_f32 v237, v237, v75, v76
	s_waitcnt lgkmcnt(6)
	v_mfma_f32_32x32x16_bf16 v[32:47], v[192:195], v[200:203], v[32:47]
	v_max3_f32 v145, v145, v93, v94
	v_max3_f32 v237, v237, v77, v78
	v_max_f32_e32 v145, v145, v95
	s_waitcnt lgkmcnt(5)
	v_mfma_f32_32x32x16_bf16 v[32:47], v[228:231], v[212:215], v[32:47]
	v_max_f32_e32 v237, v237, v79
	v_max_f32_e32 v145, v145, v237
	ds_bpermute_b32 v237, v158, v145
	s_waitcnt lgkmcnt(5)
	v_mfma_f32_32x32x16_bf16 v[32:47], v[232:235], v[216:219], v[32:47]
	v_add_u32_e32 v239, v131, v164
	s_waitcnt vmcnt(3)
	ds_write_b128 v239, v[116:119] offset:17408
	ds_read_b128 v[188:191], v147 offset:48640
	ds_read_b128 v[192:195], v147 offset:48672
	ds_read_b128 v[228:231], v147 offset:48704
	ds_read_b128 v[232:235], v147 offset:48736
	s_waitcnt lgkmcnt(9)
	v_mfma_f32_32x32x16_bf16 v[16:31], v[172:175], v[196:199], v[16:31]
	v_add_u32_e32 v239, v131, v165
	s_waitcnt vmcnt(2)
	ds_write_b128 v239, v[112:115] offset:17408
	s_waitcnt lgkmcnt(9)
	v_mfma_f32_32x32x16_bf16 v[16:31], v[176:179], v[200:203], v[16:31]
	v_add_u32_e32 v239, v156, v166
	s_waitcnt vmcnt(1)
	ds_write_b128 v239, v[124:127] offset:34816
	s_waitcnt lgkmcnt(9)
	v_mfma_f32_32x32x16_bf16 v[16:31], v[180:183], v[212:215], v[16:31]
	v_add_u32_e32 v239, v156, v167
	s_waitcnt vmcnt(0)
	ds_write_b128 v239, v[120:123] offset:34816
	s_waitcnt lgkmcnt(9)
	v_mfma_f32_32x32x16_bf16 v[16:31], v[184:187], v[216:219], v[16:31]
	s_waitcnt lgkmcnt(8)
	v_max_f32_e32 v237, v145, v237
	v_add_f32_e32 v239, 0x41000000, v149
	v_max_f32_e32 v145, v149, v237
	v_sub_f32_e32 v238, v149, v145
	v_cmp_gt_f32_e32 vcc, v237, v239
	v_exp_f32_e32 v238, v238
	s_cbranch_vccz .Lat_keepm_5
	v_mov_b32_e32 v149, v145
; __device__ __forceinline__ void phase_attn(const Params& p, unsigned char* lds) {
;     ...
;         const int toff = 2 * qb;
;         AT_LOADK(toff & 63); AT_LOADV(toff & 63); AT_STOREK(0); AT_STOREV(0);
;         __syncthreads();
;         f32x16 st[2];
;         for (int kt = 0; kt < 64; ++kt) {
;             const int buf = kt & 1;
;             if (kt + 1 < 64) { AT_LOADK((kt + 1 + toff) & 63); AT_LOADV((kt + 1 + toff) & 63); }
;             AT_QK(st, buf);
;             float mloc = st[0][0];
; #pragma unroll
;             for (int i = 0; i < 16; ++i) { mloc = fmaxf(mloc, st[0][i]); mloc = fmaxf(mloc, st[1][i]); }
;             mloc = fmaxf(mloc, __shfl_xor(mloc, 32));
;             const float mnew = fmaxf(mrun, mloc);
;             if (__builtin_amdgcn_ballot_w64(mnew > mrun) != 0ull) {
;                 const float alpha = __builtin_amdgcn_exp2f(mrun - mnew);
;                 lsum *= alpha;
; #pragma unroll
;                 for (int vb = 0; vb < 4; ++vb)
; #pragma unroll
;                     for (int i = 0; i < 16; ++i) ot[vb][i] *= alpha;
;             }
;             mrun = mnew;
;             bf16x8 P[2][2];
; #pragma unroll
;             for (int kb = 0; kb < 2; ++kb)
; #pragma unroll
;                 for (int s2 = 0; s2 < 2; ++s2) { u32x4 pk;
; #pragma unroll
;                     for (int jj = 0; jj < 4; ++jj) { const float p0 = __builtin_amdgcn_exp2f(st[kb][8 * s2 + 2 * jj] - mnew), p1 = __builtin_amdgcn_exp2f(st[kb][8 * s2 + 2 * jj + 1] - mnew); lsum += p0 + p1; pk[jj] = cvt_pk_bf16(p0, p1); }
;                     P[kb][s2] = __builtin_bit_cast(bf16x8, pk); }
;             {
;                 bf16x8 vf[2][4];
;     ...
;                 AT_LDV(0, 0);
; #pragma unroll
;                 for (int vb = 0; vb < 4; ++vb) {
;                     if (vb < 3) AT_LDV((vb + 1) & 1, vb + 1);
;                     __builtin_amdgcn_sched_barrier(0);
;                     __builtin_amdgcn_s_setprio(2);
; #pragma unroll
;                     for (int kb = 0; kb < 2; ++kb)
; #pragma unroll
;                         for (int s2 = 0; s2 < 2; ++s2) ot[vb] = __builtin_amdgcn_mfma_f32_32x32x16_bf16(vf[vb & 1][kb * 2 + s2], P[kb][s2], ot[vb], 0, 0, 0);
;                     __builtin_amdgcn_s_setprio(0);
;                     __builtin_amdgcn_sched_barrier(0);
;                 }
.Lat_keepm_5:
	s_add_i32 s21, s21, 64
	s_add_i32 s20, s20, 1
	s_waitcnt lgkmcnt(0)
	s_barrier
	ds_read_b128 v[172:175], v157 offset:17408
	ds_read_b128 v[176:179], v157 offset:17440
	ds_read_b128 v[180:183], v157 offset:17472
	ds_read_b128 v[184:187], v157 offset:17504
	s_add_i32 s12, s21, 64
	s_and_b32 s12, s12, 0xfc0
	v_add_u32_e32 v116, s12, v162
	v_ashrrev_i32_e32 v117, 31, v116
	v_add_u32_e32 v112, s12, v163
	v_lshlrev_b64 v[116:117], 13, v[116:117]
	v_ashrrev_i32_e32 v113, 31, v112
	v_lshl_add_u64 v[116:117], v[152:153], 0, v[116:117]
	v_lshlrev_b64 v[112:113], 13, v[112:113]
	v_lshl_add_u64 v[112:113], v[152:153], 0, v[112:113]
	global_load_dwordx4 v[116:119], v[116:117], off
	global_load_dwordx4 v[112:115], v[112:113], off
	s_and_b32 s12, s21, 0xfc0
	s_lshl_b32 s12, s12, 1
	v_lshl_add_u64 v[124:125], v[154:155], 0, s[12:13]
	v_lshl_add_u64 v[120:121], v[124:125], 0, v[138:139]
	v_lshl_add_u64 v[124:125], v[124:125], 0, v[136:137]
	global_load_dwordx4 v[124:127], v[124:125], off
	global_load_dwordx4 v[120:123], v[120:121], off
	s_cbranch_vccz .Lat_norescale_6
	v_pk_mul_f32 v[62:63], v[62:63], v[238:239] op_sel_hi:[1,0]
	v_pk_mul_f32 v[60:61], v[60:61], v[238:239] op_sel_hi:[1,0]
	v_pk_mul_f32 v[58:59], v[58:59], v[238:239] op_sel_hi:[1,0]
	v_pk_mul_f32 v[56:57], v[56:57], v[238:239] op_sel_hi:[1,0]
	v_pk_mul_f32 v[54:55], v[54:55], v[238:239] op_sel_hi:[1,0]
	v_pk_mul_f32 v[52:53], v[52:53], v[238:239] op_sel_hi:[1,0]
	v_pk_mul_f32 v[50:51], v[50:51], v[238:239] op_sel_hi:[1,0]
	v_pk_mul_f32 v[48:49], v[48:49], v[238:239] op_sel_hi:[1,0]
	v_pk_mul_f32 v[46:47], v[46:47], v[238:239] op_sel_hi:[1,0]
	v_pk_mul_f32 v[44:45], v[44:45], v[238:239] op_sel_hi:[1,0]
	v_pk_mul_f32 v[42:43], v[42:43], v[238:239] op_sel_hi:[1,0]
	v_pk_mul_f32 v[40:41], v[40:41], v[238:239] op_sel_hi:[1,0]
	v_pk_mul_f32 v[38:39], v[38:39], v[238:239] op_sel_hi:[1,0]
	v_pk_mul_f32 v[36:37], v[36:37], v[238:239] op_sel_hi:[1,0]
	v_pk_mul_f32 v[34:35], v[34:35], v[238:239] op_sel_hi:[1,0]
	v_pk_mul_f32 v[32:33], v[32:33], v[238:239] op_sel_hi:[1,0]
	v_pk_mul_f32 v[30:31], v[30:31], v[238:239] op_sel_hi:[1,0]
	v_pk_mul_f32 v[28:29], v[28:29], v[238:239] op_sel_hi:[1,0]
	v_pk_mul_f32 v[26:27], v[26:27], v[238:239] op_sel_hi:[1,0]
	v_pk_mul_f32 v[24:25], v[24:25], v[238:239] op_sel_hi:[1,0]
	v_pk_mul_f32 v[22:23], v[22:23], v[238:239] op_sel_hi:[1,0]
	v_pk_mul_f32 v[20:21], v[20:21], v[238:239] op_sel_hi:[1,0]
	v_pk_mul_f32 v[18:19], v[18:19], v[238:239] op_sel_hi:[1,0]
	v_pk_mul_f32 v[16:17], v[16:17], v[238:239] op_sel_hi:[1,0]
	v_mul_f32_e32 v128, v128, v238
.Lat_norescale_6:
	v_mov_b32_e32 v236, 0
	v_mfma_f32_32x32x16_bf16 v[0:15], v[188:191], v[196:199], v[0:15]
	v_sub_f32_e32 v80, v80, v149
	v_sub_f32_e32 v81, v81, v149
	v_exp_f32_e32 v80, v80
	v_exp_f32_e32 v81, v81
	v_add_f32_e32 v128, v128, v80
	v_add_f32_e32 v236, v236, v81
	v_cvt_pk_bf16_f32 v80, v80, v81
	v_sub_f32_e32 v82, v82, v149
	v_sub_f32_e32 v83, v83, v149
	v_exp_f32_e32 v82, v82
	v_exp_f32_e32 v83, v83
	v_add_f32_e32 v128, v128, v82
	v_add_f32_e32 v236, v236, v83
	v_cvt_pk_bf16_f32 v81, v82, v83
	v_mfma_f32_32x32x16_bf16 v[0:15], v[192:195], v[200:203], v[0:15]
	v_sub_f32_e32 v84, v84, v149
	v_sub_f32_e32 v85, v85, v149
	v_exp_f32_e32 v84, v84
	v_exp_f32_e32 v85, v85
	v_add_f32_e32 v128, v128, v84
	v_add_f32_e32 v236, v236, v85
	v_cvt_pk_bf16_f32 v82, v84, v85
	v_sub_f32_e32 v86, v86, v149
	v_sub_f32_e32 v87, v87, v149
	v_exp_f32_e32 v86, v86
	v_exp_f32_e32 v87, v87
	v_add_f32_e32 v128, v128, v86
	v_add_f32_e32 v236, v236, v87
	v_cvt_pk_bf16_f32 v83, v86, v87
	v_mfma_f32_32x32x16_bf16 v[0:15], v[228:231], v[212:215], v[0:15]
	v_sub_f32_e32 v88, v88, v149
	v_sub_f32_e32 v89, v89, v149
	v_exp_f32_e32 v88, v88
	v_exp_f32_e32 v89, v89
	v_add_f32_e32 v128, v128, v88
	v_add_f32_e32 v236, v236, v89
	v_cvt_pk_bf16_f32 v84, v88, v89
	v_sub_f32_e32 v90, v90, v149
	v_sub_f32_e32 v91, v91, v149
	v_exp_f32_e32 v90, v90
	v_exp_f32_e32 v91, v91
	v_add_f32_e32 v128, v128, v90
	v_add_f32_e32 v236, v236, v91
	v_cvt_pk_bf16_f32 v85, v90, v91
	v_mfma_f32_32x32x16_bf16 v[0:15], v[232:235], v[216:219], v[0:15]
	ds_read_b128 v[188:191], v157 offset:26112
	ds_read_b128 v[192:195], v157 offset:26144
	ds_read_b128 v[228:231], v157 offset:26176
	ds_read_b128 v[232:235], v157 offset:26208
	v_sub_f32_e32 v92, v92, v149
	v_sub_f32_e32 v93, v93, v149
	v_exp_f32_e32 v92, v92
	v_exp_f32_e32 v93, v93
	v_add_f32_e32 v128, v128, v92
	v_add_f32_e32 v236, v236, v93
	v_cvt_pk_bf16_f32 v86, v92, v93
	v_sub_f32_e32 v94, v94, v149
	v_sub_f32_e32 v95, v95, v149
	v_exp_f32_e32 v94, v94
	v_exp_f32_e32 v95, v95
	v_add_f32_e32 v128, v128, v94
	v_add_f32_e32 v236, v236, v95
	v_cvt_pk_bf16_f32 v87, v94, v95
	s_waitcnt lgkmcnt(7)
	v_mfma_f32_32x32x16_bf16 v[196:211], v[172:175], v[108:111], 0
	v_sub_f32_e32 v64, v64, v149
	v_sub_f32_e32 v65, v65, v149
	v_exp_f32_e32 v64, v64
	v_exp_f32_e32 v65, v65
	v_add_f32_e32 v128, v128, v64
	v_add_f32_e32 v236, v236, v65
	v_cvt_pk_bf16_f32 v64, v64, v65
	s_waitcnt lgkmcnt(6)
	v_mfma_f32_32x32x16_bf16 v[196:211], v[176:179], v[104:107], v[196:211]
	v_sub_f32_e32 v66, v66, v149
	v_sub_f32_e32 v67, v67, v149
	v_exp_f32_e32 v66, v66
	v_exp_f32_e32 v67, v67
	v_add_f32_e32 v128, v128, v66
	v_add_f32_e32 v236, v236, v67
	v_cvt_pk_bf16_f32 v65, v66, v67
	s_cbranch_vccz .Lat_norescale_7
	v_pk_mul_f32 v[14:15], v[14:15], v[238:239] op_sel_hi:[1,0]
	v_pk_mul_f32 v[12:13], v[12:13], v[238:239] op_sel_hi:[1,0]
	v_pk_mul_f32 v[10:11], v[10:11], v[238:239] op_sel_hi:[1,0]
	v_pk_mul_f32 v[8:9], v[8:9], v[238:239] op_sel_hi:[1,0]
	v_pk_mul_f32 v[6:7], v[6:7], v[238:239] op_sel_hi:[1,0]
	v_pk_mul_f32 v[4:5], v[4:5], v[238:239] op_sel_hi:[1,0]
	v_pk_mul_f32 v[2:3], v[2:3], v[238:239] op_sel_hi:[1,0]
	v_pk_mul_f32 v[0:1], v[0:1], v[238:239] op_sel_hi:[1,0]
; __device__ __forceinline__ void phase_attn(const Params& p, unsigned char* lds) {
;     ...
;         const int toff = 2 * qb;
;         AT_LOADK(toff & 63); AT_LOADV(toff & 63); AT_STOREK(0); AT_STOREV(0);
;         __syncthreads();
;         f32x16 st[2];
;         for (int kt = 0; kt < 64; ++kt) {
;             const int buf = kt & 1;
;             if (kt + 1 < 64) { AT_LOADK((kt + 1 + toff) & 63); AT_LOADV((kt + 1 + toff) & 63); }
;             AT_QK(st, buf);
;             float mloc = st[0][0];
; #pragma unroll
;             for (int i = 0; i < 16; ++i) { mloc = fmaxf(mloc, st[0][i]); mloc = fmaxf(mloc, st[1][i]); }
;             mloc = fmaxf(mloc, __shfl_xor(mloc, 32));
;             const float mnew = fmaxf(mrun, mloc);
;             if (__builtin_amdgcn_ballot_w64(mnew > mrun) != 0ull) {
;                 const float alpha = __builtin_amdgcn_exp2f(mrun - mnew);
;                 lsum *= alpha;
; #pragma unroll
;                 for (int vb = 0; vb < 4; ++vb)
; #pragma unroll
;                     for (int i = 0; i < 16; ++i) ot[vb][i] *= alpha;
;             }
;             mrun = mnew;
;             bf16x8 P[2][2];
; #pragma unroll
;             for (int kb = 0; kb < 2; ++kb)
; #pragma unroll
;                 for (int s2 = 0; s2 < 2; ++s2) { u32x4 pk;
; #pragma unroll
;                     for (int jj = 0; jj < 4; ++jj) { const float p0 = __builtin_amdgcn_exp2f(st[kb][8 * s2 + 2 * jj] - mnew), p1 = __builtin_amdgcn_exp2f(st[kb][8 * s2 + 2 * jj + 1] - mnew); lsum += p0 + p1; pk[jj] = cvt_pk_bf16(p0, p1); }
;                     P[kb][s2] = __builtin_bit_cast(bf16x8, pk); }
;             {
;                 bf16x8 vf[2][4];
;     ...
;                 AT_LDV(0, 0);
; #pragma unroll
;                 for (int vb = 0; vb < 4; ++vb) {
;                     if (vb < 3) AT_LDV((vb + 1) & 1, vb + 1);
;                     __builtin_amdgcn_sched_barrier(0);
;                     __builtin_amdgcn_s_setprio(2);
; #pragma unroll
;                     for (int kb = 0; kb < 2; ++kb)
; #pragma unroll
;                         for (int s2 = 0; s2 < 2; ++s2) ot[vb] = __builtin_amdgcn_mfma_f32_32x32x16_bf16(vf[vb & 1][kb * 2 + s2], P[kb][s2], ot[vb], 0, 0, 0);
;                     __builtin_amdgcn_s_setprio(0);
;                     __builtin_amdgcn_sched_barrier(0);
;                 }
;     ...
;             }
;             if (kt + 1 < 64) { AT_STOREK(buf ^ 1); AT_STOREV(buf ^ 1); }
.Lat_norescale_7:
	s_waitcnt lgkmcnt(5)
	v_mfma_f32_32x32x16_bf16 v[196:211], v[180:183], v[100:103], v[196:211]
	v_sub_f32_e32 v68, v68, v149
	v_sub_f32_e32 v69, v69, v149
	v_exp_f32_e32 v68, v68
	v_exp_f32_e32 v69, v69
	v_add_f32_e32 v128, v128, v68
	v_add_f32_e32 v236, v236, v69
	v_cvt_pk_bf16_f32 v66, v68, v69
	s_waitcnt lgkmcnt(4)
	v_mfma_f32_32x32x16_bf16 v[196:211], v[184:187], v[96:99], v[196:211]
	ds_read_b128 v[172:175], v159 offset:34816
	ds_read_b128 v[176:179], v159 offset:34848
	ds_read_b128 v[180:183], v159 offset:34880
	ds_read_b128 v[184:187], v159 offset:34912
	v_sub_f32_e32 v70, v70, v149
	v_sub_f32_e32 v71, v71, v149
	v_exp_f32_e32 v70, v70
	v_exp_f32_e32 v71, v71
	v_add_f32_e32 v128, v128, v70
	v_add_f32_e32 v236, v236, v71
	v_cvt_pk_bf16_f32 v67, v70, v71
	s_waitcnt lgkmcnt(7)
	v_mfma_f32_32x32x16_bf16 v[212:227], v[188:191], v[108:111], 0
	v_sub_f32_e32 v72, v72, v149
	v_sub_f32_e32 v73, v73, v149
	v_exp_f32_e32 v72, v72
	v_exp_f32_e32 v73, v73
	v_add_f32_e32 v128, v128, v72
	v_add_f32_e32 v236, v236, v73
	v_cvt_pk_bf16_f32 v68, v72, v73
	s_waitcnt lgkmcnt(6)
	v_mfma_f32_32x32x16_bf16 v[212:227], v[192:195], v[104:107], v[212:227]
	v_sub_f32_e32 v74, v74, v149
	v_sub_f32_e32 v75, v75, v149
	v_exp_f32_e32 v74, v74
	v_exp_f32_e32 v75, v75
	v_add_f32_e32 v128, v128, v74
	v_add_f32_e32 v236, v236, v75
	v_cvt_pk_bf16_f32 v69, v74, v75
	s_waitcnt lgkmcnt(5)
	v_mfma_f32_32x32x16_bf16 v[212:227], v[228:231], v[100:103], v[212:227]
	v_sub_f32_e32 v76, v76, v149
	v_sub_f32_e32 v77, v77, v149
	v_exp_f32_e32 v76, v76
	v_exp_f32_e32 v77, v77
	v_add_f32_e32 v128, v128, v76
	v_add_f32_e32 v236, v236, v77
	v_cvt_pk_bf16_f32 v70, v76, v77
	s_waitcnt lgkmcnt(4)
	v_mfma_f32_32x32x16_bf16 v[212:227], v[232:235], v[96:99], v[212:227]
	ds_read_b128 v[188:191], v159 offset:39424
	ds_read_b128 v[192:195], v159 offset:39456
	ds_read_b128 v[228:231], v159 offset:39488
	ds_read_b128 v[232:235], v159 offset:39520
	v_sub_f32_e32 v78, v78, v149
	v_sub_f32_e32 v79, v79, v149
	v_exp_f32_e32 v78, v78
	v_exp_f32_e32 v79, v79
	v_add_f32_e32 v128, v128, v78
	v_add_f32_e32 v236, v236, v79
	v_cvt_pk_bf16_f32 v71, v78, v79
	v_add_f32_e32 v128, v128, v236
	s_waitcnt lgkmcnt(7)
	v_mfma_f32_32x32x16_bf16 v[48:63], v[172:175], v[80:83], v[48:63]
	s_waitcnt lgkmcnt(6)
	v_mfma_f32_32x32x16_bf16 v[48:63], v[176:179], v[84:87], v[48:63]
	v_max3_f32 v145, v196, v197, v198
	v_max3_f32 v237, v212, v213, v214
	v_max3_f32 v145, v145, v199, v200
	s_waitcnt lgkmcnt(5)
	v_mfma_f32_32x32x16_bf16 v[48:63], v[180:183], v[64:67], v[48:63]
	v_max3_f32 v237, v237, v215, v216
	v_max3_f32 v145, v145, v201, v202
	v_max3_f32 v237, v237, v217, v218
	s_waitcnt lgkmcnt(4)
	v_mfma_f32_32x32x16_bf16 v[48:63], v[184:187], v[68:71], v[48:63]
	v_max3_f32 v145, v145, v203, v204
	v_max3_f32 v237, v237, v219, v220
	v_max3_f32 v145, v145, v205, v206
	ds_read_b128 v[172:175], v159 offset:44032
	ds_read_b128 v[176:179], v159 offset:44064
	ds_read_b128 v[180:183], v159 offset:44096
	ds_read_b128 v[184:187], v159 offset:44128
	s_waitcnt lgkmcnt(7)
	v_mfma_f32_32x32x16_bf16 v[32:47], v[188:191], v[80:83], v[32:47]
	v_max3_f32 v237, v237, v221, v222
	v_max3_f32 v145, v145, v207, v208
	v_max3_f32 v237, v237, v223, v224
	s_waitcnt lgkmcnt(6)
	v_mfma_f32_32x32x16_bf16 v[32:47], v[192:195], v[84:87], v[32:47]
	v_max3_f32 v145, v145, v209, v210
	v_max3_f32 v237, v237, v225, v226
	v_max_f32_e32 v145, v145, v211
	s_waitcnt lgkmcnt(5)
	v_mfma_f32_32x32x16_bf16 v[32:47], v[228:231], v[64:67], v[32:47]
	v_max_f32_e32 v237, v237, v227
	v_max_f32_e32 v145, v145, v237
	ds_bpermute_b32 v237, v158, v145
	s_waitcnt lgkmcnt(5)
	v_mfma_f32_32x32x16_bf16 v[32:47], v[232:235], v[68:71], v[32:47]
	v_add_u32_e32 v239, v131, v164
	s_waitcnt vmcnt(3)
	ds_write_b128 v239, v[116:119] offset:0
	ds_read_b128 v[188:191], v159 offset:48640
	ds_read_b128 v[192:195], v159 offset:48672
	ds_read_b128 v[228:231], v159 offset:48704
	ds_read_b128 v[232:235], v159 offset:48736
	s_waitcnt lgkmcnt(9)
	v_mfma_f32_32x32x16_bf16 v[16:31], v[172:175], v[80:83], v[16:31]
	v_add_u32_e32 v239, v131, v165
	s_waitcnt vmcnt(2)
	ds_write_b128 v239, v[112:115] offset:0
	s_waitcnt lgkmcnt(9)
	v_mfma_f32_32x32x16_bf16 v[16:31], v[176:179], v[84:87], v[16:31]
	v_add_u32_e32 v239, v156, v166
	s_waitcnt vmcnt(1)
	ds_write_b128 v239, v[124:127] offset:53248
	s_waitcnt lgkmcnt(9)
	v_mfma_f32_32x32x16_bf16 v[16:31], v[180:183], v[64:67], v[16:31]
	v_add_u32_e32 v239, v156, v167
	s_waitcnt vmcnt(0)
	ds_write_b128 v239, v[120:123] offset:53248
	s_waitcnt lgkmcnt(9)
	v_mfma_f32_32x32x16_bf16 v[16:31], v[184:187], v[68:71], v[16:31]
	s_waitcnt lgkmcnt(8)
	v_max_f32_e32 v237, v145, v237
	v_add_f32_e32 v239, 0x41000000, v149
	v_max_f32_e32 v145, v149, v237
	v_sub_f32_e32 v238, v149, v145
	v_cmp_gt_f32_e32 vcc, v237, v239
	v_exp_f32_e32 v238, v238
	s_cbranch_vccz .Lat_keepm_8
	v_mov_b32_e32 v149, v145
; __device__ __forceinline__ unsigned cvt_pk_bf16(float lo, float hi) { unsigned r; asm volatile("v_cvt_pk_bf16_f32 %0, %1, %2" : "=v"(r) : "v"(lo), "v"(hi)); return r; }
; __device__ __forceinline__ void phase_attn(const Params& p, unsigned char* lds) {
;     ...
;         for (int kt = 0; kt < 64; ++kt) {
;             const int buf = kt & 1;
;             if (kt + 1 < 64) { AT_LOADK((kt + 1 + toff) & 63); AT_LOADV((kt + 1 + toff) & 63); }
;             AT_QK(st, buf);
;             float mloc = st[0][0];
; #pragma unroll
;             for (int i = 0; i < 16; ++i) { mloc = fmaxf(mloc, st[0][i]); mloc = fmaxf(mloc, st[1][i]); }
;             mloc = fmaxf(mloc, __shfl_xor(mloc, 32));
;             const float mnew = fmaxf(mrun, mloc);
;             if (__builtin_amdgcn_ballot_w64(mnew > mrun) != 0ull) {
;                 const float alpha = __builtin_amdgcn_exp2f(mrun - mnew);
;                 lsum *= alpha;
; #pragma unroll
;                 for (int vb = 0; vb < 4; ++vb)
; #pragma unroll
;                     for (int i = 0; i < 16; ++i) ot[vb][i] *= alpha;
;             }
;             mrun = mnew;
;             bf16x8 P[2][2];
; #pragma unroll
;             for (int kb = 0; kb < 2; ++kb)
; #pragma unroll
;                 for (int s2 = 0; s2 < 2; ++s2) { u32x4 pk;
; #pragma unroll
;                     for (int jj = 0; jj < 4; ++jj) { const float p0 = __builtin_amdgcn_exp2f(st[kb][8 * s2 + 2 * jj] - mnew), p1 = __builtin_amdgcn_exp2f(st[kb][8 * s2 + 2 * jj + 1] - mnew); lsum += p0 + p1; pk[jj] = cvt_pk_bf16(p0, p1); }
;                     P[kb][s2] = __builtin_bit_cast(bf16x8, pk); }
;             {
;                 bf16x8 vf[2][4];
;     ...
;                 AT_LDV(0, 0);
; #pragma unroll
;                 for (int vb = 0; vb < 4; ++vb) {
;                     if (vb < 3) AT_LDV((vb + 1) & 1, vb + 1);
;                     __builtin_amdgcn_sched_barrier(0);
;                     __builtin_amdgcn_s_setprio(2);
; #pragma unroll
;                     for (int kb = 0; kb < 2; ++kb)
; #pragma unroll
;                         for (int s2 = 0; s2 < 2; ++s2) ot[vb] = __builtin_amdgcn_mfma_f32_32x32x16_bf16(vf[vb & 1][kb * 2 + s2], P[kb][s2], ot[vb], 0, 0, 0);
.Lat_keepm_8:
	s_add_i32 s21, s21, 64
	s_add_i32 s20, s20, 1
	s_waitcnt lgkmcnt(0)
	s_barrier
	s_cmp_lt_u32 s20, 63
	s_cbranch_scc1 .Lat_loop
	s_cbranch_vccz .Lat_norescale_9
	v_pk_mul_f32 v[62:63], v[62:63], v[238:239] op_sel_hi:[1,0]
	v_pk_mul_f32 v[60:61], v[60:61], v[238:239] op_sel_hi:[1,0]
	v_pk_mul_f32 v[58:59], v[58:59], v[238:239] op_sel_hi:[1,0]
	v_pk_mul_f32 v[56:57], v[56:57], v[238:239] op_sel_hi:[1,0]
	v_pk_mul_f32 v[54:55], v[54:55], v[238:239] op_sel_hi:[1,0]
	v_pk_mul_f32 v[52:53], v[52:53], v[238:239] op_sel_hi:[1,0]
	v_pk_mul_f32 v[50:51], v[50:51], v[238:239] op_sel_hi:[1,0]
	v_pk_mul_f32 v[48:49], v[48:49], v[238:239] op_sel_hi:[1,0]
	v_pk_mul_f32 v[46:47], v[46:47], v[238:239] op_sel_hi:[1,0]
	v_pk_mul_f32 v[44:45], v[44:45], v[238:239] op_sel_hi:[1,0]
	v_pk_mul_f32 v[42:43], v[42:43], v[238:239] op_sel_hi:[1,0]
	v_pk_mul_f32 v[40:41], v[40:41], v[238:239] op_sel_hi:[1,0]
	v_pk_mul_f32 v[38:39], v[38:39], v[238:239] op_sel_hi:[1,0]
	v_pk_mul_f32 v[36:37], v[36:37], v[238:239] op_sel_hi:[1,0]
	v_pk_mul_f32 v[34:35], v[34:35], v[238:239] op_sel_hi:[1,0]
	v_pk_mul_f32 v[32:33], v[32:33], v[238:239] op_sel_hi:[1,0]
	v_pk_mul_f32 v[30:31], v[30:31], v[238:239] op_sel_hi:[1,0]
	v_pk_mul_f32 v[28:29], v[28:29], v[238:239] op_sel_hi:[1,0]
	v_pk_mul_f32 v[26:27], v[26:27], v[238:239] op_sel_hi:[1,0]
	v_pk_mul_f32 v[24:25], v[24:25], v[238:239] op_sel_hi:[1,0]
	v_pk_mul_f32 v[22:23], v[22:23], v[238:239] op_sel_hi:[1,0]
	v_pk_mul_f32 v[20:21], v[20:21], v[238:239] op_sel_hi:[1,0]
	v_pk_mul_f32 v[18:19], v[18:19], v[238:239] op_sel_hi:[1,0]
	v_pk_mul_f32 v[16:17], v[16:17], v[238:239] op_sel_hi:[1,0]
	v_mul_f32_e32 v128, v128, v238
.Lat_norescale_9:
	v_mov_b32_e32 v236, 0
	v_mfma_f32_32x32x16_bf16 v[0:15], v[188:191], v[80:83], v[0:15]
	v_sub_f32_e32 v196, v196, v149
	v_sub_f32_e32 v197, v197, v149
	v_exp_f32_e32 v196, v196
	v_exp_f32_e32 v197, v197
	v_add_f32_e32 v128, v128, v196
	v_add_f32_e32 v236, v236, v197
	v_cvt_pk_bf16_f32 v196, v196, v197
	v_sub_f32_e32 v198, v198, v149
	v_sub_f32_e32 v199, v199, v149
	v_exp_f32_e32 v198, v198
	v_exp_f32_e32 v199, v199
	v_add_f32_e32 v128, v128, v198
	v_add_f32_e32 v236, v236, v199
	v_cvt_pk_bf16_f32 v197, v198, v199
	v_sub_f32_e32 v200, v200, v149
	v_sub_f32_e32 v201, v201, v149
	v_exp_f32_e32 v200, v200
	v_exp_f32_e32 v201, v201
	v_add_f32_e32 v128, v128, v200
	v_add_f32_e32 v236, v236, v201
	v_cvt_pk_bf16_f32 v198, v200, v201
	v_sub_f32_e32 v202, v202, v149
	v_sub_f32_e32 v203, v203, v149
	v_exp_f32_e32 v202, v202
	v_exp_f32_e32 v203, v203
	v_add_f32_e32 v128, v128, v202
	v_add_f32_e32 v236, v236, v203
	v_cvt_pk_bf16_f32 v199, v202, v203
	v_mfma_f32_32x32x16_bf16 v[0:15], v[192:195], v[84:87], v[0:15]
	v_sub_f32_e32 v204, v204, v149
	v_sub_f32_e32 v205, v205, v149
	v_exp_f32_e32 v204, v204
	v_exp_f32_e32 v205, v205
	v_add_f32_e32 v128, v128, v204
	v_add_f32_e32 v236, v236, v205
	v_cvt_pk_bf16_f32 v200, v204, v205
	v_sub_f32_e32 v206, v206, v149
	v_sub_f32_e32 v207, v207, v149
	v_exp_f32_e32 v206, v206
	v_exp_f32_e32 v207, v207
	v_add_f32_e32 v128, v128, v206
	v_add_f32_e32 v236, v236, v207
	v_cvt_pk_bf16_f32 v201, v206, v207
	v_sub_f32_e32 v208, v208, v149
	v_sub_f32_e32 v209, v209, v149
	v_exp_f32_e32 v208, v208
	v_exp_f32_e32 v209, v209
	v_add_f32_e32 v128, v128, v208
	v_add_f32_e32 v236, v236, v209
	v_cvt_pk_bf16_f32 v202, v208, v209
	v_sub_f32_e32 v210, v210, v149
	v_sub_f32_e32 v211, v211, v149
	v_exp_f32_e32 v210, v210
	v_exp_f32_e32 v211, v211
	v_add_f32_e32 v128, v128, v210
	v_add_f32_e32 v236, v236, v211
	v_cvt_pk_bf16_f32 v203, v210, v211
	v_mfma_f32_32x32x16_bf16 v[0:15], v[228:231], v[64:67], v[0:15]
	v_sub_f32_e32 v212, v212, v149
	v_sub_f32_e32 v213, v213, v149
	v_exp_f32_e32 v212, v212
	v_exp_f32_e32 v213, v213
	v_add_f32_e32 v128, v128, v212
	v_add_f32_e32 v236, v236, v213
	v_cvt_pk_bf16_f32 v212, v212, v213
	v_sub_f32_e32 v214, v214, v149
	v_sub_f32_e32 v215, v215, v149
	v_exp_f32_e32 v214, v214
	v_exp_f32_e32 v215, v215
	v_add_f32_e32 v128, v128, v214
	v_add_f32_e32 v236, v236, v215
	v_cvt_pk_bf16_f32 v213, v214, v215
	v_sub_f32_e32 v216, v216, v149
	v_sub_f32_e32 v217, v217, v149
	v_exp_f32_e32 v216, v216
	v_exp_f32_e32 v217, v217
	v_add_f32_e32 v128, v128, v216
	v_add_f32_e32 v236, v236, v217
	v_cvt_pk_bf16_f32 v214, v216, v217
	v_sub_f32_e32 v218, v218, v149
	v_sub_f32_e32 v219, v219, v149
	v_exp_f32_e32 v218, v218
	v_exp_f32_e32 v219, v219
	v_add_f32_e32 v128, v128, v218
	v_add_f32_e32 v236, v236, v219
	v_cvt_pk_bf16_f32 v215, v218, v219
	v_mfma_f32_32x32x16_bf16 v[0:15], v[232:235], v[68:71], v[0:15]
	v_sub_f32_e32 v220, v220, v149
	v_sub_f32_e32 v221, v221, v149
	v_exp_f32_e32 v220, v220
	v_exp_f32_e32 v221, v221
	v_add_f32_e32 v128, v128, v220
	v_add_f32_e32 v236, v236, v221
	v_cvt_pk_bf16_f32 v216, v220, v221
	v_sub_f32_e32 v222, v222, v149
	v_sub_f32_e32 v223, v223, v149
	v_exp_f32_e32 v222, v222
	v_exp_f32_e32 v223, v223
	v_add_f32_e32 v128, v128, v222
	v_add_f32_e32 v236, v236, v223
	v_cvt_pk_bf16_f32 v217, v222, v223
	v_sub_f32_e32 v224, v224, v149
	v_sub_f32_e32 v225, v225, v149
	v_exp_f32_e32 v224, v224
	v_exp_f32_e32 v225, v225
	v_add_f32_e32 v128, v128, v224
	v_add_f32_e32 v236, v236, v225
	v_cvt_pk_bf16_f32 v218, v224, v225
	v_sub_f32_e32 v226, v226, v149
	v_sub_f32_e32 v227, v227, v149
	v_exp_f32_e32 v226, v226
	v_exp_f32_e32 v227, v227
	v_add_f32_e32 v128, v128, v226
	v_add_f32_e32 v236, v236, v227
	v_cvt_pk_bf16_f32 v219, v226, v227
	s_cbranch_vccz .Lat_norescale_10
	v_pk_mul_f32 v[14:15], v[14:15], v[238:239] op_sel_hi:[1,0]
	v_pk_mul_f32 v[12:13], v[12:13], v[238:239] op_sel_hi:[1,0]
	v_pk_mul_f32 v[10:11], v[10:11], v[238:239] op_sel_hi:[1,0]
	v_pk_mul_f32 v[8:9], v[8:9], v[238:239] op_sel_hi:[1,0]
	v_pk_mul_f32 v[6:7], v[6:7], v[238:239] op_sel_hi:[1,0]
	v_pk_mul_f32 v[4:5], v[4:5], v[238:239] op_sel_hi:[1,0]
	v_pk_mul_f32 v[2:3], v[2:3], v[238:239] op_sel_hi:[1,0]
	v_pk_mul_f32 v[0:1], v[0:1], v[238:239] op_sel_hi:[1,0]
; #define AT_STOREK(buf) do { _Pragma("unroll") for (int i_ = 0; i_ < 2; ++i_) { const int id_ = tid + 512 * i_; \
;             *(u32x4*)(sKt + (buf) * 8704 + (id_ >> 4) * 136 + (id_ & 15) * 8) = kr[i_]; } } while (0)
; #define AT_STOREV(buf) do { _Pragma("unroll") for (int i_ = 0; i_ < 2; ++i_) { const int id_ = tid + 512 * i_; \
;             *(u32x4*)(sVt + (buf) * 9216 + (id_ >> 3) * 72 + (id_ & 7) * 8) = vr[i_]; } } while (0)
; #define AT_LDV(set, vb) do { _Pragma("unroll") for (int kb = 0; kb < 2; ++kb) _Pragma("unroll") for (int s2 = 0; s2 < 2; ++s2) \
;                     vf[set][kb * 2 + s2] = *(const bf16x8*)(sVt + buf * 9216 + (32 * (vb) + ql) * 72 + 32 * kb + 16 * s2 + 8 * g); } while (0)
; __device__ __forceinline__ void phase_attn(const Params& p, unsigned char* lds) {
;     ...
;                 AT_LDV(0, 0);
; #pragma unroll
;                 for (int vb = 0; vb < 4; ++vb) {
;                     if (vb < 3) AT_LDV((vb + 1) & 1, vb + 1);
;                     __builtin_amdgcn_sched_barrier(0);
;                     __builtin_amdgcn_s_setprio(2);
; #pragma unroll
;                     for (int kb = 0; kb < 2; ++kb)
; #pragma unroll
;                         for (int s2 = 0; s2 < 2; ++s2) ot[vb] = __builtin_amdgcn_mfma_f32_32x32x16_bf16(vf[vb & 1][kb * 2 + s2], P[kb][s2], ot[vb], 0, 0, 0);
;                     __builtin_amdgcn_s_setprio(0);
;                     __builtin_amdgcn_sched_barrier(0);
;                 }
;     ...
;             }
;             if (kt + 1 < 64) { AT_STOREK(buf ^ 1); AT_STOREV(buf ^ 1); }
;             __syncthreads();
;         }
;     ...
;         lsum += __shfl_xor(lsum, 32);
;         const float inv = 1.0f / lsum;
;         if (cmap == 1) {
; #pragma unroll
;             for (int vb = 0; vb < 4; ++vb)
; #pragma unroll
;                 for (int i = 0; i < 16; ++i) ex[(vb * 16 + i) * 256 + qsub * 64 + lane] = ot[vb][i] * inv;
.Lat_norescale_10:
	ds_read_b128 v[172:175], v147 offset:34816
	ds_read_b128 v[176:179], v147 offset:34848
	ds_read_b128 v[180:183], v147 offset:34880
	ds_read_b128 v[184:187], v147 offset:34912
	ds_read_b128 v[188:191], v147 offset:39424
	ds_read_b128 v[192:195], v147 offset:39456
	ds_read_b128 v[228:231], v147 offset:39488
	ds_read_b128 v[232:235], v147 offset:39520
	v_add_f32_e32 v128, v128, v236
	s_waitcnt lgkmcnt(7)
	v_mfma_f32_32x32x16_bf16 v[48:63], v[172:175], v[196:199], v[48:63]
	s_waitcnt lgkmcnt(6)
	v_mfma_f32_32x32x16_bf16 v[48:63], v[176:179], v[200:203], v[48:63]
	s_waitcnt lgkmcnt(5)
	v_mfma_f32_32x32x16_bf16 v[48:63], v[180:183], v[212:215], v[48:63]
	s_waitcnt lgkmcnt(4)
	v_mfma_f32_32x32x16_bf16 v[48:63], v[184:187], v[216:219], v[48:63]
	ds_read_b128 v[172:175], v147 offset:44032
	ds_read_b128 v[176:179], v147 offset:44064
	ds_read_b128 v[180:183], v147 offset:44096
	ds_read_b128 v[184:187], v147 offset:44128
	s_waitcnt lgkmcnt(7)
	v_mfma_f32_32x32x16_bf16 v[32:47], v[188:191], v[196:199], v[32:47]
	s_waitcnt lgkmcnt(6)
	v_mfma_f32_32x32x16_bf16 v[32:47], v[192:195], v[200:203], v[32:47]
	s_waitcnt lgkmcnt(5)
	v_mfma_f32_32x32x16_bf16 v[32:47], v[228:231], v[212:215], v[32:47]
	s_waitcnt lgkmcnt(4)
	v_mfma_f32_32x32x16_bf16 v[32:47], v[232:235], v[216:219], v[32:47]
	ds_read_b128 v[188:191], v147 offset:48640
	ds_read_b128 v[192:195], v147 offset:48672
	ds_read_b128 v[228:231], v147 offset:48704
	ds_read_b128 v[232:235], v147 offset:48736
	s_waitcnt lgkmcnt(7)
	v_mfma_f32_32x32x16_bf16 v[16:31], v[172:175], v[196:199], v[16:31]
	s_waitcnt lgkmcnt(6)
	v_mfma_f32_32x32x16_bf16 v[16:31], v[176:179], v[200:203], v[16:31]
	s_waitcnt lgkmcnt(5)
	v_mfma_f32_32x32x16_bf16 v[16:31], v[180:183], v[212:215], v[16:31]
	s_waitcnt lgkmcnt(4)
	v_mfma_f32_32x32x16_bf16 v[16:31], v[184:187], v[216:219], v[16:31]
	s_waitcnt lgkmcnt(3)
	v_mfma_f32_32x32x16_bf16 v[0:15], v[188:191], v[196:199], v[0:15]
	s_waitcnt lgkmcnt(2)
	v_mfma_f32_32x32x16_bf16 v[0:15], v[192:195], v[200:203], v[0:15]
	s_waitcnt lgkmcnt(1)
	v_mfma_f32_32x32x16_bf16 v[0:15], v[228:231], v[212:215], v[0:15]
	s_waitcnt lgkmcnt(0)
	v_mfma_f32_32x32x16_bf16 v[0:15], v[232:235], v[216:219], v[0:15]
	v_mov_b32_e32 v64, v128
	ds_bpermute_b32 v65, v158, v64
	s_waitcnt lgkmcnt(0)
	s_barrier
	v_add_f32_e32 v64, v64, v65
	v_div_scale_f32 v65, s[20:21], v64, v64, 1.0
	v_rcp_f32_e32 v66, v65
	v_div_scale_f32 v67, vcc, 1.0, v64, 1.0
	v_fma_f32 v68, -v65, v66, 1.0
	v_fmac_f32_e32 v66, v68, v66
	v_mul_f32_e32 v68, v67, v66
	v_fma_f32 v69, -v65, v68, v67
	v_fmac_f32_e32 v68, v69, v66
	v_fma_f32 v65, -v65, v68, v67
	v_div_fmas_f32 v65, v65, v66, v68
	v_div_fixup_f32 v64, v65, v64, 1.0
	s_and_saveexec_b64 s[20:21], s[4:5]
	s_cbranch_execz .LBB0_2029
	v_mul_f32_e32 v65, v48, v64
	v_mul_f32_e32 v66, v49, v64
	ds_write2st64_b32 v160, v65, v66 offset1:4
	v_mul_f32_e32 v65, v50, v64
	v_mul_f32_e32 v66, v51, v64
	ds_write2st64_b32 v160, v65, v66 offset0:8 offset1:12
	v_mul_f32_e32 v65, v52, v64
	v_mul_f32_e32 v66, v53, v64
	ds_write2st64_b32 v160, v65, v66 offset0:16 offset1:20
	v_mul_f32_e32 v65, v54, v64
	v_mul_f32_e32 v66, v55, v64
	ds_write2st64_b32 v160, v65, v66 offset0:24 offset1:28
	v_mul_f32_e32 v65, v56, v64
	v_mul_f32_e32 v66, v57, v64
	ds_write2st64_b32 v160, v65, v66 offset0:32 offset1:36
	v_mul_f32_e32 v65, v58, v64
	v_mul_f32_e32 v66, v59, v64
	ds_write2st64_b32 v160, v65, v66 offset0:40 offset1:44
	v_mul_f32_e32 v65, v60, v64
	v_mul_f32_e32 v66, v61, v64
	ds_write2st64_b32 v160, v65, v66 offset0:48 offset1:52
	v_mul_f32_e32 v65, v62, v64
	v_mul_f32_e32 v66, v63, v64
	ds_write2st64_b32 v160, v65, v66 offset0:56 offset1:60
	v_mul_f32_e32 v65, v32, v64
	v_mul_f32_e32 v66, v33, v64
	ds_write2st64_b32 v160, v65, v66 offset0:64 offset1:68
	v_mul_f32_e32 v65, v34, v64
	v_mul_f32_e32 v66, v35, v64
	ds_write2st64_b32 v160, v65, v66 offset0:72 offset1:76
	v_mul_f32_e32 v65, v36, v64
	v_mul_f32_e32 v66, v37, v64
	ds_write2st64_b32 v160, v65, v66 offset0:80 offset1:84
	v_mul_f32_e32 v65, v38, v64
	v_mul_f32_e32 v66, v39, v64
	ds_write2st64_b32 v160, v65, v66 offset0:88 offset1:92
	v_mul_f32_e32 v65, v40, v64
	v_mul_f32_e32 v66, v41, v64
	ds_write2st64_b32 v160, v65, v66 offset0:96 offset1:100
	v_mul_f32_e32 v65, v42, v64
	v_mul_f32_e32 v66, v43, v64
	ds_write2st64_b32 v160, v65, v66 offset0:104 offset1:108
	v_mul_f32_e32 v65, v44, v64
	v_mul_f32_e32 v66, v45, v64
	ds_write2st64_b32 v160, v65, v66 offset0:112 offset1:116
	v_mul_f32_e32 v65, v46, v64
	v_mul_f32_e32 v66, v47, v64
	ds_write2st64_b32 v160, v65, v66 offset0:120 offset1:124
	v_mul_f32_e32 v65, v16, v64
	v_mul_f32_e32 v66, v17, v64
	ds_write2st64_b32 v160, v65, v66 offset0:128 offset1:132
	v_mul_f32_e32 v65, v18, v64
	v_mul_f32_e32 v66, v19, v64
	ds_write2st64_b32 v160, v65, v66 offset0:136 offset1:140
	v_mul_f32_e32 v65, v20, v64
	v_mul_f32_e32 v66, v21, v64
	ds_write2st64_b32 v160, v65, v66 offset0:144 offset1:148
	v_mul_f32_e32 v65, v22, v64
	v_mul_f32_e32 v66, v23, v64
	ds_write2st64_b32 v160, v65, v66 offset0:152 offset1:156
	v_mul_f32_e32 v65, v24, v64
	v_mul_f32_e32 v66, v25, v64
	ds_write2st64_b32 v160, v65, v66 offset0:160 offset1:164
	v_mul_f32_e32 v65, v26, v64
	v_mul_f32_e32 v66, v27, v64
	ds_write2st64_b32 v160, v65, v66 offset0:168 offset1:172
	v_mul_f32_e32 v65, v28, v64
	v_mul_f32_e32 v66, v29, v64
	ds_write2st64_b32 v160, v65, v66 offset0:176 offset1:180
	v_mul_f32_e32 v65, v30, v64
	v_mul_f32_e32 v66, v31, v64
	ds_write2st64_b32 v160, v65, v66 offset0:184 offset1:188
	v_mul_f32_e32 v65, v0, v64
	v_mul_f32_e32 v66, v1, v64
	ds_write2st64_b32 v160, v65, v66 offset0:192 offset1:196
	v_mul_f32_e32 v65, v2, v64
	v_mul_f32_e32 v66, v3, v64
	ds_write2st64_b32 v160, v65, v66 offset0:200 offset1:204
	v_mul_f32_e32 v65, v4, v64
	v_mul_f32_e32 v66, v5, v64
	ds_write2st64_b32 v160, v65, v66 offset0:208 offset1:212
	v_mul_f32_e32 v65, v6, v64
	v_mul_f32_e32 v66, v7, v64
	ds_write2st64_b32 v160, v65, v66 offset0:216 offset1:220
	v_mul_f32_e32 v65, v8, v64
	v_mul_f32_e32 v66, v9, v64
	ds_write2st64_b32 v160, v65, v66 offset0:224 offset1:228
	v_mul_f32_e32 v65, v10, v64
	v_mul_f32_e32 v66, v11, v64
	ds_write2st64_b32 v160, v65, v66 offset0:232 offset1:236
	v_mul_f32_e32 v65, v12, v64
	v_mul_f32_e32 v66, v13, v64
	ds_write2st64_b32 v160, v65, v66 offset0:240 offset1:244
	v_mul_f32_e32 v65, v14, v64
	v_mul_f32_e32 v66, v15, v64
	ds_write2st64_b32 v160, v65, v66 offset0:248 offset1:252
